# baseline (speedup 1.0000x reference)
; #define GAS __attribute__((address_space(1)))
; __device__ __forceinline__ int ugrid() { return __builtin_amdgcn_readfirstlane((int)gridDim.x); }
; __device__ __forceinline__ int ubid() { return __builtin_amdgcn_readfirstlane((int)blockIdx.x); }
; __device__ __forceinline__ void phase_inproj() {
;     ...
;       for (int r0 = ubid() * 64 + w * 16; r0 < T; r0 += ugrid() * 64) {
;         const GAS bf16x8* ap = (const GAS bf16x8*)(xg + (size_t)(r0 + fr_) * DM + fq_ * 8);
;         const GAS bf16x8* bp = (const GAS bf16x8*)(wf + (size_t)(fr_ & 7) * DM + fq_ * 8);
;         f32x4 c = {0.f, 0.f, 0.f, 0.f};
; #pragma unroll
;         for (int kb = 0; kb < 2; ++kb) {
;           bf16x8 a[16], b[16];
; #pragma unroll
;           for (int k = 0; k < 16; ++k) { a[k] = ap[(kb * 16 + k) * 4]; b[k] = bp[(kb * 16 + k) * 4]; }
; #pragma unroll
;           for (int k = 0; k < 16; ++k) c = __builtin_amdgcn_mfma_f32_16x16x32_bf16(a[k], b[k], c, 0, 0, 0);
;         }
.LBB0_378:
	v_or_b32_e32 v2, v7, v6
	v_ashrrev_i32_e32 v3, 31, v2
	v_lshlrev_b64 v[2:3], 11, v[2:3]
	v_lshl_add_u64 v[86:87], v[10:11], 0, v[2:3]
	s_load_dwordx2 s[4:5], s[6:7], 0x40
	global_load_dwordx4 v[14:17], v[86:87], off
	global_load_dwordx4 v[26:29], v[12:13], off
	global_load_dwordx4 v[30:33], v[86:87], off offset:64
	global_load_dwordx4 v[34:37], v[12:13], off offset:64
	global_load_dwordx4 v[38:41], v[86:87], off offset:128
	global_load_dwordx4 v[42:45], v[12:13], off offset:128
	global_load_dwordx4 v[46:49], v[86:87], off offset:192
	global_load_dwordx4 v[50:53], v[12:13], off offset:192
	global_load_dwordx4 v[54:57], v[86:87], off offset:256
	global_load_dwordx4 v[58:61], v[12:13], off offset:256
	global_load_dwordx4 v[62:65], v[86:87], off offset:320
	global_load_dwordx4 v[66:69], v[12:13], off offset:320
	global_load_dwordx4 v[70:73], v[86:87], off offset:384
	global_load_dwordx4 v[74:77], v[12:13], off offset:384
	global_load_dwordx4 v[78:81], v[86:87], off offset:448
	global_load_dwordx4 v[82:85], v[12:13], off offset:448
	global_load_dwordx4 v[88:91], v[86:87], off offset:512
	global_load_dwordx4 v[92:95], v[12:13], off offset:512
	global_load_dwordx4 v[96:99], v[86:87], off offset:576
	global_load_dwordx4 v[100:103], v[12:13], off offset:576
	global_load_dwordx4 v[104:107], v[86:87], off offset:640
	global_load_dwordx4 v[108:111], v[12:13], off offset:640
	global_load_dwordx4 v[112:115], v[86:87], off offset:704
	global_load_dwordx4 v[116:119], v[12:13], off offset:704
	global_load_dwordx4 v[120:123], v[86:87], off offset:768
	global_load_dwordx4 v[124:127], v[12:13], off offset:768
	global_load_dwordx4 v[128:131], v[86:87], off offset:832
	global_load_dwordx4 v[132:135], v[12:13], off offset:832
	global_load_dwordx4 v[136:139], v[86:87], off offset:896
	global_load_dwordx4 v[140:143], v[12:13], off offset:896
	global_load_dwordx4 v[144:147], v[86:87], off offset:960
	global_load_dwordx4 v[148:151], v[12:13], off offset:960
	global_load_dwordx4 v[152:155], v[86:87], off offset:1024
	global_load_dwordx4 v[156:159], v[12:13], off offset:1024
	global_load_dwordx4 v[160:163], v[86:87], off offset:1088
	global_load_dwordx4 v[164:167], v[12:13], off offset:1088
	global_load_dwordx4 v[176:179], v[86:87], off offset:1152
	global_load_dwordx4 v[180:183], v[12:13], off offset:1152
	global_load_dwordx4 v[184:187], v[86:87], off offset:1216
	global_load_dwordx4 v[188:191], v[12:13], off offset:1216
	global_load_dwordx4 v[192:195], v[86:87], off offset:1280
	global_load_dwordx4 v[196:199], v[12:13], off offset:1280
	global_load_dwordx4 v[200:203], v[86:87], off offset:1344
	global_load_dwordx4 v[204:207], v[12:13], off offset:1344
	global_load_dwordx4 v[208:211], v[86:87], off offset:1408
	global_load_dwordx4 v[212:215], v[12:13], off offset:1408
	global_load_dwordx4 v[216:219], v[86:87], off offset:1472
	global_load_dwordx4 v[220:223], v[12:13], off offset:1472
	global_load_dwordx4 v[224:227], v[86:87], off offset:1536
	global_load_dwordx4 v[228:231], v[12:13], off offset:1536
	global_load_dwordx4 v[232:235], v[86:87], off offset:1600
	global_load_dwordx4 v[236:239], v[12:13], off offset:1600
	s_waitcnt vmcnt(40)
	v_mfma_f32_16x16x32_bf16 v[2:5], v[14:17], v[26:29], 0
	v_mfma_f32_16x16x32_bf16 v[2:5], v[30:33], v[34:37], v[2:5]
	v_mfma_f32_16x16x32_bf16 v[2:5], v[38:41], v[42:45], v[2:5]
	v_mfma_f32_16x16x32_bf16 v[2:5], v[46:49], v[50:53], v[2:5]
	v_mfma_f32_16x16x32_bf16 v[2:5], v[54:57], v[58:61], v[2:5]
	v_mfma_f32_16x16x32_bf16 v[2:5], v[62:65], v[66:69], v[2:5]
	global_load_dwordx4 v[14:17], v[86:87], off offset:1664
	global_load_dwordx4 v[26:29], v[12:13], off offset:1664
	global_load_dwordx4 v[30:33], v[86:87], off offset:1728
	global_load_dwordx4 v[34:37], v[12:13], off offset:1728
	global_load_dwordx4 v[38:41], v[86:87], off offset:1792
	global_load_dwordx4 v[42:45], v[12:13], off offset:1792
	global_load_dwordx4 v[46:49], v[86:87], off offset:1856
	global_load_dwordx4 v[50:53], v[12:13], off offset:1856
	global_load_dwordx4 v[54:57], v[86:87], off offset:1920
	global_load_dwordx4 v[58:61], v[12:13], off offset:1920
	global_load_dwordx4 v[62:65], v[86:87], off offset:1984
	global_load_dwordx4 v[66:69], v[12:13], off offset:1984
	s_waitcnt vmcnt(50)
	v_mfma_f32_16x16x32_bf16 v[2:5], v[70:73], v[74:77], v[2:5]
	s_waitcnt vmcnt(48)
	v_mfma_f32_16x16x32_bf16 v[2:5], v[78:81], v[82:85], v[2:5]
	s_waitcnt vmcnt(46)
	v_mfma_f32_16x16x32_bf16 v[2:5], v[88:91], v[92:95], v[2:5]
	s_waitcnt vmcnt(44)
	v_mfma_f32_16x16x32_bf16 v[2:5], v[96:99], v[100:103], v[2:5]
	s_waitcnt vmcnt(42)
	v_mfma_f32_16x16x32_bf16 v[2:5], v[104:107], v[108:111], v[2:5]
	s_waitcnt vmcnt(40)
	v_mfma_f32_16x16x32_bf16 v[2:5], v[112:115], v[116:119], v[2:5]
	s_waitcnt vmcnt(38)
	v_mfma_f32_16x16x32_bf16 v[2:5], v[120:123], v[124:127], v[2:5]
	s_waitcnt vmcnt(36)
	v_mfma_f32_16x16x32_bf16 v[2:5], v[128:131], v[132:135], v[2:5]
	s_waitcnt vmcnt(34)
	v_mfma_f32_16x16x32_bf16 v[2:5], v[136:139], v[140:143], v[2:5]
	s_waitcnt vmcnt(32)
	v_mfma_f32_16x16x32_bf16 v[2:5], v[144:147], v[148:151], v[2:5]
	s_waitcnt vmcnt(30)
	v_mfma_f32_16x16x32_bf16 v[2:5], v[152:155], v[156:159], v[2:5]
	s_waitcnt vmcnt(28)
	v_mfma_f32_16x16x32_bf16 v[2:5], v[160:163], v[164:167], v[2:5]
	s_waitcnt vmcnt(26)
	v_mfma_f32_16x16x32_bf16 v[2:5], v[176:179], v[180:183], v[2:5]
	s_waitcnt vmcnt(24)
	v_mfma_f32_16x16x32_bf16 v[2:5], v[184:187], v[188:191], v[2:5]
	s_waitcnt vmcnt(22)
	v_mfma_f32_16x16x32_bf16 v[2:5], v[192:195], v[196:199], v[2:5]
	s_waitcnt vmcnt(20)
	v_mfma_f32_16x16x32_bf16 v[2:5], v[200:203], v[204:207], v[2:5]
	s_waitcnt vmcnt(18)
	v_mfma_f32_16x16x32_bf16 v[2:5], v[208:211], v[212:215], v[2:5]
	s_waitcnt vmcnt(16)
	v_mfma_f32_16x16x32_bf16 v[2:5], v[216:219], v[220:223], v[2:5]
	s_waitcnt vmcnt(14)
	v_mfma_f32_16x16x32_bf16 v[2:5], v[224:227], v[228:231], v[2:5]
	s_waitcnt vmcnt(12)
	v_mfma_f32_16x16x32_bf16 v[2:5], v[232:235], v[236:239], v[2:5]
	s_waitcnt vmcnt(10)
	v_mfma_f32_16x16x32_bf16 v[2:5], v[14:17], v[26:29], v[2:5]
	s_waitcnt vmcnt(8)
	v_mfma_f32_16x16x32_bf16 v[2:5], v[30:33], v[34:37], v[2:5]
	s_waitcnt vmcnt(6)
	v_mfma_f32_16x16x32_bf16 v[2:5], v[38:41], v[42:45], v[2:5]
	s_waitcnt vmcnt(4)
	v_mfma_f32_16x16x32_bf16 v[2:5], v[46:49], v[50:53], v[2:5]
	s_waitcnt vmcnt(2)
	v_mfma_f32_16x16x32_bf16 v[2:5], v[54:57], v[58:61], v[2:5]
	s_waitcnt vmcnt(0)
	v_mfma_f32_16x16x32_bf16 v[2:5], v[62:65], v[66:69], v[2:5]
	s_and_saveexec_b64 s[12:13], vcc
	s_cbranch_execz .LBB0_377
; #define GAS __attribute__((address_space(1)))
; __device__ __forceinline__ void phase_inproj() {
;     ...
;         if (fr_ < 8) {
;           const float bias = ((const GAS float*)P.forget_bias)[fr_];
; #pragma unroll
;           for (int i = 0; i < 4; ++i) {
;             const int row = r0 + fq_ * 4 + i;
;             const GAS f32x4* sp = (const GAS f32x4*)(ssq + (size_t)row * 16);
;             const f32x4 s0 = sp[0], s1 = sp[1], s2 = sp[2], s3 = sp[3];
;             const float t = ((s0.x + s0.y) + (s0.z + s0.w)) + ((s1.x + s1.y) + (s1.z + s1.w)) + ((s2.x + s2.y) + (s2.z + s2.w)) + ((s3.x + s3.y) + (s3.z + s3.w));
;             const float l = c[i] * rsqrtf(t * (1.f / DM) + EPS) + bias;
;             const float ls = fminf(l, 0.f) - log1pf(__expf(-fabsf(l)));
;             logf2[(size_t)((row >> 13) * 8 + fr_) * SEQ + (row & (SEQ - 1))] = ls * LOG2E;
;           }
	v_or_b32_e32 v14, v7, v18
	v_ashrrev_i32_e32 v15, 31, v14
	v_lshlrev_b64 v[16:17], 6, v[14:15]
	v_lshl_add_u64 v[16:17], s[8:9], 0, v[16:17]
	global_load_dwordx4 v[26:29], v[16:17], off
	global_load_dwordx4 v[30:33], v[16:17], off offset:16
	global_load_dwordx4 v[34:37], v[16:17], off offset:32
	global_load_dwordx4 v[38:41], v[16:17], off offset:48
	global_load_dwordx4 v[88:91], v[16:17], off offset:64
	global_load_dwordx4 v[92:95], v[16:17], off offset:80
	global_load_dwordx4 v[96:99], v[16:17], off offset:96
	global_load_dwordx4 v[100:103], v[16:17], off offset:112
	global_load_dwordx4 v[104:107], v[16:17], off offset:128
	global_load_dwordx4 v[108:111], v[16:17], off offset:144
	global_load_dwordx4 v[112:115], v[16:17], off offset:160
	global_load_dwordx4 v[116:119], v[16:17], off offset:176
	global_load_dwordx4 v[120:123], v[16:17], off offset:192
	global_load_dwordx4 v[124:127], v[16:17], off offset:208
	global_load_dwordx4 v[128:131], v[16:17], off offset:224
	global_load_dwordx4 v[132:135], v[16:17], off offset:240
	v_ashrrev_i32_e32 v8, 10, v7
	v_bitop3_b32 v17, v7, s23, v18 bitop3:0xc8
	v_and_or_b32 v16, v8, -8, v6
	v_lshlrev_b32_e32 v8, 2, v17
	s_waitcnt lgkmcnt(0)
	global_load_dword v15, v19, s[4:5]
	v_or_b32_e32 v42, 1, v14
	v_ashrrev_i32_e32 v17, 31, v16
	v_ashrrev_i32_e32 v43, 31, v42
	v_lshlrev_b64 v[16:17], 15, v[16:17]
	v_lshl_add_u64 v[16:17], s[16:17], 0, v[16:17]
	s_waitcnt vmcnt(16)
	v_mov_b32_e32 v44, v27
	v_mov_b32_e32 v45, v28
	v_mov_b32_e32 v27, v29
	s_waitcnt vmcnt(15)
	v_mov_b32_e32 v28, v31
	v_mov_b32_e32 v29, v32
	v_mov_b32_e32 v31, v33
	v_pk_add_f32 v[26:27], v[44:45], v[26:27]
	v_pk_add_f32 v[28:29], v[28:29], v[30:31]
	v_pk_add_f32 v[26:27], v[26:27], v[26:27] op_sel:[0,1] op_sel_hi:[1,0]
	v_pk_add_f32 v[28:29], v[28:29], v[28:29] op_sel:[0,1] op_sel_hi:[1,0]
	s_waitcnt vmcnt(14)
	v_add_f32_e32 v32, v34, v35
	v_add_f32_e32 v34, v36, v37
	s_waitcnt vmcnt(13)
	v_mov_b32_e32 v33, v40
	v_mov_b32_e32 v35, v41
	v_mov_b32_e32 v27, v38
	v_mov_b32_e32 v29, v39
	v_pk_add_f32 v[30:31], v[32:33], v[34:35]
	v_pk_add_f32 v[26:27], v[26:27], v[28:29]
	s_nop 0
	v_pk_add_f32 v[26:27], v[26:27], v[30:31]
	s_nop 0
	v_add_f32_e32 v25, v26, v27
	v_fmamk_f32 v25, v25, 0x3a800000, v20
	v_mul_f32_e32 v26, 0x4b800000, v25
	v_cmp_gt_f32_e64 s[4:5], s3, v25
	s_nop 1
	v_cndmask_b32_e64 v25, v25, v26, s[4:5]
	v_rsq_f32_e32 v25, v25
	v_lshlrev_b64 v[26:27], 6, v[42:43]
	v_lshl_add_u64 v[42:43], s[8:9], 0, v[26:27]
	v_lshl_add_u64 v[26:27], v[16:17], 0, v[8:9]
	v_mul_f32_e32 v28, 0x45800000, v25
	v_cndmask_b32_e64 v25, v25, v28, s[4:5]
	s_waitcnt vmcnt(0)
	v_fma_f32 v2, v2, v25, v15
	v_mul_f32_e64 v25, |v2|, s18
	v_exp_f32_e32 v25, v25
	v_min_f32_e32 v2, 0, v2
	v_add_f32_e32 v8, 1.0, v25
	v_add_f32_e32 v30, -1.0, v8
	v_frexp_mant_f32_e32 v31, v8
	v_cvt_f64_f32_e32 v[28:29], v8
	v_sub_f32_e32 v32, v30, v8
	v_frexp_exp_i32_f64_e32 v28, v[28:29]
	v_cmp_gt_f32_e64 s[4:5], s19, v31
	v_sub_f32_e32 v30, v25, v30
	v_add_f32_e32 v29, 1.0, v32
	v_subbrev_co_u32_e64 v28, s[4:5], 0, v28, s[4:5]
	v_add_f32_e32 v29, v30, v29
	v_sub_u32_e32 v30, 0, v28
	v_cvt_f32_i32_e32 v28, v28
	v_ldexp_f32 v8, v8, v30
	v_ldexp_f32 v29, v29, v30
	v_add_f32_e32 v30, -1.0, v8
	v_add_f32_e32 v31, 1.0, v8
	v_add_f32_e32 v32, 1.0, v30
	v_add_f32_e32 v33, -1.0, v31
	v_sub_f32_e32 v32, v8, v32
	v_sub_f32_e32 v8, v8, v33
	v_mul_f32_e32 v33, 0x3f317218, v28
	v_add_f32_e32 v32, v29, v32
	v_add_f32_e32 v8, v29, v8
	v_fma_f32 v29, v28, s20, -v33
	v_add_f32_e32 v34, v30, v32
	v_add_f32_e32 v35, v31, v8
	v_fmac_f32_e32 v29, 0xb102e308, v28
	v_sub_f32_e32 v28, v34, v30
	v_sub_f32_e32 v30, v35, v31
	v_rcp_f32_e32 v31, v35
	v_add_f32_e32 v36, v33, v29
	v_sub_f32_e32 v8, v8, v30
	v_sub_f32_e32 v30, v36, v33
	v_sub_f32_e32 v29, v29, v30
	v_mul_f32_e32 v30, v34, v31
	v_sub_f32_e32 v28, v32, v28
	v_mul_f32_e32 v32, v35, v30
	v_fma_f32 v33, v30, v35, -v32
	v_fmac_f32_e32 v33, v30, v8
	v_add_f32_e32 v37, v32, v33
	v_sub_f32_e32 v38, v34, v37
	v_sub_f32_e32 v32, v37, v32
	v_sub_f32_e32 v34, v34, v38
	v_sub_f32_e32 v32, v32, v33
	v_sub_f32_e32 v33, v34, v37
	v_add_f32_e32 v28, v28, v33
	v_add_f32_e32 v28, v32, v28
	v_add_f32_e32 v32, v38, v28
	v_mul_f32_e32 v33, v31, v32
	v_sub_f32_e32 v34, v38, v32
	v_mul_f32_e32 v37, v35, v33
	v_add_f32_e32 v28, v28, v34
	v_add_f32_e32 v34, v30, v33
	v_fma_f32 v35, v33, v35, -v37
	v_sub_f32_e32 v30, v34, v30
	v_fmac_f32_e32 v35, v33, v8
	v_sub_f32_e32 v8, v33, v30
	v_add_f32_e32 v30, v37, v35
	v_sub_f32_e32 v33, v30, v37
	v_sub_f32_e32 v37, v32, v30
	v_sub_f32_e32 v32, v32, v37
	v_sub_f32_e32 v30, v32, v30
	v_sub_f32_e32 v33, v33, v35
	v_add_f32_e32 v28, v28, v30
	v_add_f32_e32 v28, v33, v28
	v_add_f32_e32 v28, v37, v28
	v_mul_f32_e32 v28, v31, v28
	v_add_f32_e32 v8, v8, v28
	v_add_f32_e32 v28, v34, v8
	v_mul_f32_e32 v30, v28, v28
	v_fmamk_f32 v33, v30, 0x3e9b6dac, v21
	v_sub_f32_e32 v31, v28, v34
	v_ldexp_f32 v32, v28, 1
	v_mul_f32_e32 v28, v28, v30
	v_fmaak_f32 v30, v30, v33, 0x3f2aaada
	v_mul_f32_e32 v28, v28, v30
	v_add_f32_e32 v30, v32, v28
	v_sub_f32_e32 v8, v8, v31
	v_sub_f32_e32 v31, v30, v32
	v_ldexp_f32 v8, v8, 1
	v_sub_f32_e32 v28, v28, v31
	v_add_f32_e32 v8, v8, v28
	v_add_f32_e32 v28, v30, v8
	v_sub_f32_e32 v30, v28, v30
	v_add_f32_e32 v31, v36, v28
	v_sub_f32_e32 v8, v8, v30
	v_sub_f32_e32 v30, v31, v36
	v_sub_f32_e32 v32, v31, v30
	v_sub_f32_e32 v28, v28, v30
	v_add_f32_e32 v30, v29, v8
	v_sub_f32_e32 v32, v36, v32
	v_sub_f32_e32 v33, v30, v29
	v_add_f32_e32 v28, v28, v32
	v_sub_f32_e32 v32, v30, v33
	v_sub_f32_e32 v8, v8, v33
	v_sub_f32_e32 v29, v29, v32
	v_add_f32_e32 v28, v30, v28
	v_add_f32_e32 v8, v8, v29
	v_add_f32_e32 v29, v31, v28
	v_sub_f32_e32 v30, v29, v31
	v_sub_f32_e32 v28, v28, v30
	v_add_f32_e32 v8, v8, v28
	v_add_f32_e32 v8, v29, v8
	v_cmp_neq_f32_e64 s[4:5], s21, v25
	s_nop 1
	v_cndmask_b32_e64 v8, v22, v8, s[4:5]
	v_cmp_ngt_f32_e64 s[4:5], -1.0, v25
	s_nop 1
	v_cndmask_b32_e64 v8, v23, v8, s[4:5]
	v_cmp_neq_f32_e64 s[4:5], -1.0, v25
	s_nop 1
	v_cndmask_b32_e64 v8, v24, v8, s[4:5]
	v_cmp_lt_f32_e64 s[4:5], |v25|, s22
	s_nop 1
	v_cndmask_b32_e64 v8, v8, v25, s[4:5]
	v_sub_f32_e32 v2, v2, v8
	v_mul_f32_e32 v2, 0x3fb8aa3b, v2
	global_store_dword v[26:27], v2, off
	s_nop 1
	v_mov_b64_e32 v[26:27], v[88:89]
	v_mov_b64_e32 v[28:29], v[90:91]
	v_mov_b64_e32 v[30:31], v[92:93]
	v_mov_b64_e32 v[32:33], v[94:95]
	v_mov_b64_e32 v[34:35], v[96:97]
	v_mov_b64_e32 v[36:37], v[98:99]
	v_mov_b64_e32 v[38:39], v[100:101]
	v_mov_b64_e32 v[40:41], v[102:103]
	v_bitop3_b32 v2, v14, s24, 1 bitop3:0xc8
	v_or_b32_e32 v42, 2, v14
	v_ashrrev_i32_e32 v43, 31, v42
	s_waitcnt vmcnt(3)
; #define GAS __attribute__((address_space(1)))
; __device__ __forceinline__ void phase_inproj() {
;     ...
;           for (int i = 0; i < 4; ++i) {
;             const int row = r0 + fq_ * 4 + i;
;             const GAS f32x4* sp = (const GAS f32x4*)(ssq + (size_t)row * 16);
;             const f32x4 s0 = sp[0], s1 = sp[1], s2 = sp[2], s3 = sp[3];
;             const float t = ((s0.x + s0.y) + (s0.z + s0.w)) + ((s1.x + s1.y) + (s1.z + s1.w)) + ((s2.x + s2.y) + (s2.z + s2.w)) + ((s3.x + s3.y) + (s3.z + s3.w));
;             const float l = c[i] * rsqrtf(t * (1.f / DM) + EPS) + bias;
;             const float ls = fminf(l, 0.f) - log1pf(__expf(-fabsf(l)));
;             logf2[(size_t)((row >> 13) * 8 + fr_) * SEQ + (row & (SEQ - 1))] = ls * LOG2E;
;           }
	v_mov_b32_e32 v44, v27
	v_mov_b32_e32 v45, v28
	v_mov_b32_e32 v27, v29
	s_waitcnt vmcnt(2)
	v_mov_b32_e32 v28, v31
	v_mov_b32_e32 v29, v32
	v_mov_b32_e32 v31, v33
	v_pk_add_f32 v[26:27], v[44:45], v[26:27]
	v_pk_add_f32 v[28:29], v[28:29], v[30:31]
	v_pk_add_f32 v[26:27], v[26:27], v[26:27] op_sel:[0,1] op_sel_hi:[1,0]
	v_pk_add_f32 v[28:29], v[28:29], v[28:29] op_sel:[0,1] op_sel_hi:[1,0]
	s_waitcnt vmcnt(1)
	v_add_f32_e32 v32, v34, v35
	v_add_f32_e32 v34, v36, v37
	s_waitcnt vmcnt(0)
	v_mov_b32_e32 v33, v40
	v_mov_b32_e32 v35, v41
	v_mov_b32_e32 v27, v38
	v_mov_b32_e32 v29, v39
	v_pk_add_f32 v[30:31], v[32:33], v[34:35]
	v_pk_add_f32 v[26:27], v[26:27], v[28:29]
	s_nop 0
	v_pk_add_f32 v[26:27], v[26:27], v[30:31]
	s_nop 0
	v_add_f32_e32 v8, v26, v27
	v_fmamk_f32 v8, v8, 0x3a800000, v20
	v_mul_f32_e32 v25, 0x4b800000, v8
	v_cmp_gt_f32_e64 s[4:5], s3, v8
	v_lshlrev_b64 v[26:27], 6, v[42:43]
	v_lshl_add_u64 v[42:43], s[8:9], 0, v[26:27]
	v_cndmask_b32_e64 v8, v8, v25, s[4:5]
	v_rsq_f32_e32 v8, v8
	s_nop 0
	v_mul_f32_e32 v25, 0x45800000, v8
	v_cndmask_b32_e64 v8, v8, v25, s[4:5]
	v_fma_f32 v25, v3, v8, v15
	v_mul_f32_e64 v3, |v25|, s18
	v_exp_f32_e32 v28, v3
	v_lshlrev_b32_e32 v8, 2, v2
	v_lshl_add_u64 v[2:3], v[16:17], 0, v[8:9]
	v_min_f32_e32 v8, 0, v25
	v_add_f32_e32 v25, 1.0, v28
	v_add_f32_e32 v29, -1.0, v25
	v_frexp_mant_f32_e32 v30, v25
	v_cvt_f64_f32_e32 v[26:27], v25
	v_sub_f32_e32 v31, v29, v25
	v_frexp_exp_i32_f64_e32 v26, v[26:27]
	v_cmp_gt_f32_e64 s[4:5], s19, v30
	v_sub_f32_e32 v29, v28, v29
	v_add_f32_e32 v27, 1.0, v31
	v_subbrev_co_u32_e64 v26, s[4:5], 0, v26, s[4:5]
	v_add_f32_e32 v27, v29, v27
	v_sub_u32_e32 v29, 0, v26
	v_cvt_f32_i32_e32 v26, v26
	v_ldexp_f32 v25, v25, v29
	v_ldexp_f32 v27, v27, v29
	v_add_f32_e32 v29, -1.0, v25
	v_add_f32_e32 v30, 1.0, v25
	v_add_f32_e32 v31, 1.0, v29
	v_add_f32_e32 v32, -1.0, v30
	v_sub_f32_e32 v31, v25, v31
	v_sub_f32_e32 v25, v25, v32
	v_mul_f32_e32 v32, 0x3f317218, v26
	v_add_f32_e32 v31, v27, v31
	v_add_f32_e32 v25, v27, v25
	v_fma_f32 v27, v26, s20, -v32
	v_add_f32_e32 v33, v29, v31
	v_add_f32_e32 v34, v30, v25
	v_fmac_f32_e32 v27, 0xb102e308, v26
	v_sub_f32_e32 v26, v33, v29
	v_sub_f32_e32 v29, v34, v30
	v_rcp_f32_e32 v30, v34
	v_add_f32_e32 v35, v32, v27
	v_sub_f32_e32 v25, v25, v29
	v_sub_f32_e32 v29, v35, v32
	v_sub_f32_e32 v27, v27, v29
	v_mul_f32_e32 v29, v33, v30
	v_sub_f32_e32 v26, v31, v26
	v_mul_f32_e32 v31, v34, v29
	v_fma_f32 v32, v29, v34, -v31
	v_fmac_f32_e32 v32, v29, v25
	v_add_f32_e32 v36, v31, v32
	v_sub_f32_e32 v37, v33, v36
	v_sub_f32_e32 v31, v36, v31
	v_sub_f32_e32 v33, v33, v37
	v_sub_f32_e32 v31, v31, v32
	v_sub_f32_e32 v32, v33, v36
	v_add_f32_e32 v26, v26, v32
	v_add_f32_e32 v26, v31, v26
	v_add_f32_e32 v31, v37, v26
	v_mul_f32_e32 v32, v30, v31
	v_sub_f32_e32 v33, v37, v31
	v_mul_f32_e32 v36, v34, v32
	v_add_f32_e32 v26, v26, v33
	v_add_f32_e32 v33, v29, v32
	v_fma_f32 v34, v32, v34, -v36
	v_sub_f32_e32 v29, v33, v29
	v_fmac_f32_e32 v34, v32, v25
	v_sub_f32_e32 v25, v32, v29
	v_add_f32_e32 v29, v36, v34
	v_sub_f32_e32 v32, v29, v36
	v_sub_f32_e32 v36, v31, v29
	v_sub_f32_e32 v31, v31, v36
	v_sub_f32_e32 v29, v31, v29
	v_sub_f32_e32 v32, v32, v34
	v_add_f32_e32 v26, v26, v29
	v_add_f32_e32 v26, v32, v26
	v_add_f32_e32 v26, v36, v26
	v_mul_f32_e32 v26, v30, v26
	v_add_f32_e32 v25, v25, v26
	v_add_f32_e32 v26, v33, v25
	v_mul_f32_e32 v29, v26, v26
	v_fmamk_f32 v32, v29, 0x3e9b6dac, v21
	v_sub_f32_e32 v30, v26, v33
	v_ldexp_f32 v31, v26, 1
	v_mul_f32_e32 v26, v26, v29
	v_fmaak_f32 v29, v29, v32, 0x3f2aaada
	v_mul_f32_e32 v26, v26, v29
	v_add_f32_e32 v29, v31, v26
	v_sub_f32_e32 v25, v25, v30
	v_sub_f32_e32 v30, v29, v31
	v_ldexp_f32 v25, v25, 1
	v_sub_f32_e32 v26, v26, v30
	v_add_f32_e32 v25, v25, v26
	v_add_f32_e32 v26, v29, v25
	v_sub_f32_e32 v29, v26, v29
	v_add_f32_e32 v30, v35, v26
	v_sub_f32_e32 v25, v25, v29
	v_sub_f32_e32 v29, v30, v35
	v_sub_f32_e32 v31, v30, v29
	v_sub_f32_e32 v26, v26, v29
	v_add_f32_e32 v29, v27, v25
	v_sub_f32_e32 v31, v35, v31
	v_sub_f32_e32 v32, v29, v27
	v_add_f32_e32 v26, v26, v31
	v_sub_f32_e32 v31, v29, v32
	v_sub_f32_e32 v25, v25, v32
	v_sub_f32_e32 v27, v27, v31
	v_add_f32_e32 v26, v29, v26
	v_add_f32_e32 v25, v25, v27
	v_add_f32_e32 v27, v30, v26
	v_sub_f32_e32 v29, v27, v30
	v_sub_f32_e32 v26, v26, v29
	v_add_f32_e32 v25, v25, v26
	v_add_f32_e32 v25, v27, v25
	v_cmp_neq_f32_e64 s[4:5], s21, v28
	s_nop 1
	v_cndmask_b32_e64 v25, v22, v25, s[4:5]
	v_cmp_ngt_f32_e64 s[4:5], -1.0, v28
	s_nop 1
	v_cndmask_b32_e64 v25, v23, v25, s[4:5]
	v_cmp_neq_f32_e64 s[4:5], -1.0, v28
	s_nop 1
	v_cndmask_b32_e64 v25, v24, v25, s[4:5]
	v_cmp_lt_f32_e64 s[4:5], |v28|, s22
	s_nop 1
	v_cndmask_b32_e64 v25, v25, v28, s[4:5]
	v_sub_f32_e32 v8, v8, v25
	v_mul_f32_e32 v8, 0x3fb8aa3b, v8
	global_store_dword v[2:3], v8, off
	s_nop 1
	v_mov_b64_e32 v[26:27], v[104:105]
	v_mov_b64_e32 v[28:29], v[106:107]
	v_mov_b64_e32 v[30:31], v[108:109]
	v_mov_b64_e32 v[32:33], v[110:111]
	v_mov_b64_e32 v[34:35], v[112:113]
	v_mov_b64_e32 v[36:37], v[114:115]
	v_mov_b64_e32 v[38:39], v[116:117]
	v_mov_b64_e32 v[40:41], v[118:119]
	v_bitop3_b32 v8, v14, s25, 2 bitop3:0xc8
	v_lshlrev_b32_e32 v8, 2, v8
	v_or_b32_e32 v2, 3, v14
	s_waitcnt vmcnt(3)
	v_mov_b32_e32 v42, v27
	v_mov_b32_e32 v43, v28
	v_mov_b32_e32 v27, v29
	s_waitcnt vmcnt(2)
	v_mov_b32_e32 v28, v31
	v_mov_b32_e32 v29, v32
	v_mov_b32_e32 v31, v33
	v_pk_add_f32 v[26:27], v[42:43], v[26:27]
	v_pk_add_f32 v[28:29], v[28:29], v[30:31]
	v_pk_add_f32 v[26:27], v[26:27], v[26:27] op_sel:[0,1] op_sel_hi:[1,0]
	v_pk_add_f32 v[28:29], v[28:29], v[28:29] op_sel:[0,1] op_sel_hi:[1,0]
	s_waitcnt vmcnt(1)
; #define GAS __attribute__((address_space(1)))
; __device__ __forceinline__ void phase_inproj() {
;     ...
;           for (int i = 0; i < 4; ++i) {
;             const int row = r0 + fq_ * 4 + i;
;             const GAS f32x4* sp = (const GAS f32x4*)(ssq + (size_t)row * 16);
;             const f32x4 s0 = sp[0], s1 = sp[1], s2 = sp[2], s3 = sp[3];
;             const float t = ((s0.x + s0.y) + (s0.z + s0.w)) + ((s1.x + s1.y) + (s1.z + s1.w)) + ((s2.x + s2.y) + (s2.z + s2.w)) + ((s3.x + s3.y) + (s3.z + s3.w));
;             const float l = c[i] * rsqrtf(t * (1.f / DM) + EPS) + bias;
;             const float ls = fminf(l, 0.f) - log1pf(__expf(-fabsf(l)));
;             logf2[(size_t)((row >> 13) * 8 + fr_) * SEQ + (row & (SEQ - 1))] = ls * LOG2E;
;           }
	v_add_f32_e32 v32, v34, v35
	v_add_f32_e32 v34, v36, v37
	s_waitcnt vmcnt(0)
	v_mov_b32_e32 v33, v40
	v_mov_b32_e32 v35, v41
	v_mov_b32_e32 v27, v38
	v_mov_b32_e32 v29, v39
	v_pk_add_f32 v[30:31], v[32:33], v[34:35]
	v_pk_add_f32 v[26:27], v[26:27], v[28:29]
	s_nop 0
	v_pk_add_f32 v[26:27], v[26:27], v[30:31]
	s_nop 0
	v_add_f32_e32 v3, v26, v27
	v_fmamk_f32 v3, v3, 0x3a800000, v20
	v_mul_f32_e32 v25, 0x4b800000, v3
	v_cmp_gt_f32_e64 s[4:5], s3, v3
	s_nop 1
	v_cndmask_b32_e64 v3, v3, v25, s[4:5]
	v_rsq_f32_e32 v25, v3
	v_ashrrev_i32_e32 v3, 31, v2
	v_lshlrev_b64 v[2:3], 6, v[2:3]
	v_lshl_add_u64 v[2:3], s[8:9], 0, v[2:3]
	v_mul_f32_e32 v26, 0x45800000, v25
	v_cndmask_b32_e64 v25, v25, v26, s[4:5]
	v_fma_f32 v4, v4, v25, v15
	v_mul_f32_e64 v25, |v4|, s18
	v_exp_f32_e32 v25, v25
	v_lshl_add_u64 v[26:27], v[16:17], 0, v[8:9]
	v_min_f32_e32 v4, 0, v4
	v_add_f32_e32 v8, 1.0, v25
	v_add_f32_e32 v30, -1.0, v8
	v_frexp_mant_f32_e32 v31, v8
	v_cvt_f64_f32_e32 v[28:29], v8
	v_sub_f32_e32 v32, v30, v8
	v_frexp_exp_i32_f64_e32 v28, v[28:29]
	v_cmp_gt_f32_e64 s[4:5], s19, v31
	v_sub_f32_e32 v30, v25, v30
	v_add_f32_e32 v29, 1.0, v32
	v_subbrev_co_u32_e64 v28, s[4:5], 0, v28, s[4:5]
	v_add_f32_e32 v29, v30, v29
	v_sub_u32_e32 v30, 0, v28
	v_cvt_f32_i32_e32 v28, v28
	v_ldexp_f32 v8, v8, v30
	v_ldexp_f32 v29, v29, v30
	v_add_f32_e32 v30, -1.0, v8
	v_add_f32_e32 v31, 1.0, v8
	v_add_f32_e32 v32, 1.0, v30
	v_add_f32_e32 v33, -1.0, v31
	v_sub_f32_e32 v32, v8, v32
	v_sub_f32_e32 v8, v8, v33
	v_mul_f32_e32 v33, 0x3f317218, v28
	v_add_f32_e32 v32, v29, v32
	v_add_f32_e32 v8, v29, v8
	v_fma_f32 v29, v28, s20, -v33
	v_add_f32_e32 v34, v30, v32
	v_add_f32_e32 v35, v31, v8
	v_fmac_f32_e32 v29, 0xb102e308, v28
	v_sub_f32_e32 v28, v34, v30
	v_sub_f32_e32 v30, v35, v31
	v_rcp_f32_e32 v31, v35
	v_add_f32_e32 v36, v33, v29
	v_sub_f32_e32 v8, v8, v30
	v_sub_f32_e32 v30, v36, v33
	v_sub_f32_e32 v29, v29, v30
	v_mul_f32_e32 v30, v34, v31
	v_sub_f32_e32 v28, v32, v28
	v_mul_f32_e32 v32, v35, v30
	v_fma_f32 v33, v30, v35, -v32
	v_fmac_f32_e32 v33, v30, v8
	v_add_f32_e32 v37, v32, v33
	v_sub_f32_e32 v38, v34, v37
	v_sub_f32_e32 v32, v37, v32
	v_sub_f32_e32 v34, v34, v38
	v_sub_f32_e32 v32, v32, v33
	v_sub_f32_e32 v33, v34, v37
	v_add_f32_e32 v28, v28, v33
	v_add_f32_e32 v28, v32, v28
	v_add_f32_e32 v32, v38, v28
	v_mul_f32_e32 v33, v31, v32
	v_sub_f32_e32 v34, v38, v32
	v_mul_f32_e32 v37, v35, v33
	v_add_f32_e32 v28, v28, v34
	v_add_f32_e32 v34, v30, v33
	v_fma_f32 v35, v33, v35, -v37
	v_sub_f32_e32 v30, v34, v30
	v_fmac_f32_e32 v35, v33, v8
	v_sub_f32_e32 v8, v33, v30
	v_add_f32_e32 v30, v37, v35
	v_sub_f32_e32 v33, v30, v37
	v_sub_f32_e32 v37, v32, v30
	v_sub_f32_e32 v32, v32, v37
	v_sub_f32_e32 v30, v32, v30
	v_sub_f32_e32 v33, v33, v35
	v_add_f32_e32 v28, v28, v30
	v_add_f32_e32 v28, v33, v28
	v_add_f32_e32 v28, v37, v28
	v_mul_f32_e32 v28, v31, v28
	v_add_f32_e32 v8, v8, v28
	v_add_f32_e32 v28, v34, v8
	v_mul_f32_e32 v30, v28, v28
	v_fmamk_f32 v33, v30, 0x3e9b6dac, v21
	v_sub_f32_e32 v31, v28, v34
	v_ldexp_f32 v32, v28, 1
	v_mul_f32_e32 v28, v28, v30
	v_fmaak_f32 v30, v30, v33, 0x3f2aaada
	v_mul_f32_e32 v28, v28, v30
	v_add_f32_e32 v30, v32, v28
	v_sub_f32_e32 v8, v8, v31
	v_sub_f32_e32 v31, v30, v32
	v_ldexp_f32 v8, v8, 1
	v_sub_f32_e32 v28, v28, v31
	v_add_f32_e32 v8, v8, v28
	v_add_f32_e32 v28, v30, v8
	v_sub_f32_e32 v30, v28, v30
	v_add_f32_e32 v31, v36, v28
	v_sub_f32_e32 v8, v8, v30
	v_sub_f32_e32 v30, v31, v36
	v_sub_f32_e32 v32, v31, v30
	v_sub_f32_e32 v28, v28, v30
	v_add_f32_e32 v30, v29, v8
	v_sub_f32_e32 v32, v36, v32
	v_sub_f32_e32 v33, v30, v29
	v_add_f32_e32 v28, v28, v32
	v_sub_f32_e32 v32, v30, v33
	v_sub_f32_e32 v8, v8, v33
	v_sub_f32_e32 v29, v29, v32
	v_add_f32_e32 v28, v30, v28
	v_add_f32_e32 v8, v8, v29
	v_add_f32_e32 v29, v31, v28
	v_sub_f32_e32 v30, v29, v31
	v_sub_f32_e32 v28, v28, v30
	v_add_f32_e32 v8, v8, v28
	v_add_f32_e32 v8, v29, v8
	v_cmp_neq_f32_e64 s[4:5], s21, v25
	s_nop 1
	v_cndmask_b32_e64 v8, v22, v8, s[4:5]
	v_cmp_ngt_f32_e64 s[4:5], -1.0, v25
	s_nop 1
	v_cndmask_b32_e64 v8, v23, v8, s[4:5]
	v_cmp_neq_f32_e64 s[4:5], -1.0, v25
	s_nop 1
	v_cndmask_b32_e64 v8, v24, v8, s[4:5]
	v_cmp_lt_f32_e64 s[4:5], |v25|, s22
	s_nop 1
	v_cndmask_b32_e64 v8, v8, v25, s[4:5]
	v_sub_f32_e32 v4, v4, v8
	v_mul_f32_e32 v4, 0x3fb8aa3b, v4
	global_store_dword v[26:27], v4, off
	s_nop 1
	v_mov_b64_e32 v[26:27], v[120:121]
	v_mov_b64_e32 v[28:29], v[122:123]
	v_mov_b64_e32 v[30:31], v[124:125]
	v_mov_b64_e32 v[32:33], v[126:127]
	v_mov_b64_e32 v[34:35], v[128:129]
	v_mov_b64_e32 v[36:37], v[130:131]
	v_mov_b64_e32 v[38:39], v[132:133]
	v_mov_b64_e32 v[40:41], v[134:135]
	s_waitcnt vmcnt(3)
; #define GAS __attribute__((address_space(1)))
; __device__ __forceinline__ void phase_inproj() {
;     ...
;           for (int i = 0; i < 4; ++i) {
;             const int row = r0 + fq_ * 4 + i;
;             const GAS f32x4* sp = (const GAS f32x4*)(ssq + (size_t)row * 16);
;             const f32x4 s0 = sp[0], s1 = sp[1], s2 = sp[2], s3 = sp[3];
;             const float t = ((s0.x + s0.y) + (s0.z + s0.w)) + ((s1.x + s1.y) + (s1.z + s1.w)) + ((s2.x + s2.y) + (s2.z + s2.w)) + ((s3.x + s3.y) + (s3.z + s3.w));
;             const float l = c[i] * rsqrtf(t * (1.f / DM) + EPS) + bias;
;             const float ls = fminf(l, 0.f) - log1pf(__expf(-fabsf(l)));
;             logf2[(size_t)((row >> 13) * 8 + fr_) * SEQ + (row & (SEQ - 1))] = ls * LOG2E;
;           }
	v_mov_b32_e32 v2, v27
	v_mov_b32_e32 v3, v28
	v_mov_b32_e32 v27, v29
	s_waitcnt vmcnt(2)
	v_mov_b32_e32 v28, v31
	v_mov_b32_e32 v29, v32
	v_mov_b32_e32 v31, v33
	v_pk_add_f32 v[2:3], v[2:3], v[26:27]
	v_pk_add_f32 v[26:27], v[28:29], v[30:31]
	v_pk_add_f32 v[2:3], v[2:3], v[2:3] op_sel:[0,1] op_sel_hi:[1,0]
	v_pk_add_f32 v[26:27], v[26:27], v[26:27] op_sel:[0,1] op_sel_hi:[1,0]
	s_waitcnt vmcnt(1)
	v_add_f32_e32 v32, v34, v35
	v_add_f32_e32 v34, v36, v37
	s_waitcnt vmcnt(0)
	v_mov_b32_e32 v33, v40
	v_mov_b32_e32 v35, v41
	v_mov_b32_e32 v3, v38
	v_mov_b32_e32 v27, v39
	v_pk_add_f32 v[28:29], v[32:33], v[34:35]
	v_pk_add_f32 v[2:3], v[2:3], v[26:27]
	s_nop 0
	v_pk_add_f32 v[2:3], v[2:3], v[28:29]
	s_nop 0
	v_add_f32_e32 v2, v2, v3
	v_fmamk_f32 v2, v2, 0x3a800000, v20
	v_mul_f32_e32 v3, 0x4b800000, v2
	v_cmp_gt_f32_e64 s[4:5], s3, v2
	s_nop 1
	v_cndmask_b32_e64 v2, v2, v3, s[4:5]
	v_rsq_f32_e32 v2, v2
	s_nop 0
	v_mul_f32_e32 v3, 0x45800000, v2
	v_cndmask_b32_e64 v2, v2, v3, s[4:5]
	v_fmac_f32_e32 v15, v5, v2
	v_mul_f32_e64 v2, |v15|, s18
	v_exp_f32_e32 v4, v2
	v_bitop3_b32 v2, v14, s26, 3 bitop3:0xc8
	v_lshlrev_b32_e32 v8, 2, v2
	v_min_f32_e32 v5, 0, v15
	v_add_f32_e32 v14, 1.0, v4
	v_add_f32_e32 v15, -1.0, v14
	v_frexp_mant_f32_e32 v25, v14
	v_cvt_f64_f32_e32 v[2:3], v14
	v_sub_f32_e32 v26, v15, v14
	v_frexp_exp_i32_f64_e32 v2, v[2:3]
	v_cmp_gt_f32_e64 s[4:5], s19, v25
	v_sub_f32_e32 v15, v4, v15
	v_add_f32_e32 v3, 1.0, v26
	v_subbrev_co_u32_e64 v2, s[4:5], 0, v2, s[4:5]
	v_add_f32_e32 v3, v15, v3
	v_sub_u32_e32 v15, 0, v2
	v_cvt_f32_i32_e32 v2, v2
	v_ldexp_f32 v14, v14, v15
	v_ldexp_f32 v3, v3, v15
	v_add_f32_e32 v15, -1.0, v14
	v_add_f32_e32 v25, 1.0, v14
	v_add_f32_e32 v26, 1.0, v15
	v_add_f32_e32 v27, -1.0, v25
	v_sub_f32_e32 v26, v14, v26
	v_sub_f32_e32 v14, v14, v27
	v_mul_f32_e32 v27, 0x3f317218, v2
	v_add_f32_e32 v26, v3, v26
	v_add_f32_e32 v3, v3, v14
	v_fma_f32 v14, v2, s20, -v27
	v_add_f32_e32 v28, v15, v26
	v_add_f32_e32 v29, v25, v3
	v_fmac_f32_e32 v14, 0xb102e308, v2
	v_sub_f32_e32 v2, v28, v15
	v_sub_f32_e32 v15, v29, v25
	v_rcp_f32_e32 v25, v29
	v_add_f32_e32 v30, v27, v14
	v_sub_f32_e32 v3, v3, v15
	v_sub_f32_e32 v15, v30, v27
	v_sub_f32_e32 v14, v14, v15
	v_mul_f32_e32 v15, v28, v25
	v_sub_f32_e32 v2, v26, v2
	v_mul_f32_e32 v26, v29, v15
	v_fma_f32 v27, v15, v29, -v26
	v_fmac_f32_e32 v27, v15, v3
	v_add_f32_e32 v31, v26, v27
	v_sub_f32_e32 v32, v28, v31
	v_sub_f32_e32 v26, v31, v26
	v_sub_f32_e32 v28, v28, v32
	v_sub_f32_e32 v26, v26, v27
	v_sub_f32_e32 v27, v28, v31
	v_add_f32_e32 v2, v2, v27
	v_add_f32_e32 v2, v26, v2
	v_add_f32_e32 v26, v32, v2
	v_mul_f32_e32 v27, v25, v26
	v_sub_f32_e32 v28, v32, v26
	v_mul_f32_e32 v31, v29, v27
	v_add_f32_e32 v2, v2, v28
	v_add_f32_e32 v28, v15, v27
	v_fma_f32 v29, v27, v29, -v31
	v_sub_f32_e32 v15, v28, v15
	v_fmac_f32_e32 v29, v27, v3
	v_sub_f32_e32 v3, v27, v15
	v_add_f32_e32 v15, v31, v29
	v_sub_f32_e32 v27, v15, v31
	v_sub_f32_e32 v31, v26, v15
	v_sub_f32_e32 v26, v26, v31
	v_sub_f32_e32 v15, v26, v15
	v_sub_f32_e32 v27, v27, v29
	v_add_f32_e32 v2, v2, v15
	v_add_f32_e32 v2, v27, v2
	v_add_f32_e32 v2, v31, v2
	v_mul_f32_e32 v2, v25, v2
	v_add_f32_e32 v2, v3, v2
	v_add_f32_e32 v3, v28, v2
	v_mul_f32_e32 v15, v3, v3
	v_fmamk_f32 v27, v15, 0x3e9b6dac, v21
	v_sub_f32_e32 v25, v3, v28
	v_ldexp_f32 v26, v3, 1
	v_mul_f32_e32 v3, v3, v15
	v_fmaak_f32 v15, v15, v27, 0x3f2aaada
	v_mul_f32_e32 v3, v3, v15
	v_add_f32_e32 v15, v26, v3
	v_sub_f32_e32 v2, v2, v25
	v_sub_f32_e32 v25, v15, v26
	v_ldexp_f32 v2, v2, 1
	v_sub_f32_e32 v3, v3, v25
	v_add_f32_e32 v2, v2, v3
	v_add_f32_e32 v3, v15, v2
	v_sub_f32_e32 v15, v3, v15
	v_add_f32_e32 v25, v30, v3
	v_sub_f32_e32 v2, v2, v15
	v_sub_f32_e32 v15, v25, v30
	v_sub_f32_e32 v26, v25, v15
	v_sub_f32_e32 v3, v3, v15
	v_add_f32_e32 v15, v14, v2
	v_sub_f32_e32 v26, v30, v26
	v_sub_f32_e32 v27, v15, v14
	v_add_f32_e32 v3, v3, v26
	v_sub_f32_e32 v26, v15, v27
	v_sub_f32_e32 v2, v2, v27
	v_sub_f32_e32 v14, v14, v26
	v_add_f32_e32 v3, v15, v3
	v_add_f32_e32 v2, v2, v14
	v_add_f32_e32 v14, v25, v3
	v_sub_f32_e32 v15, v14, v25
	v_sub_f32_e32 v3, v3, v15
	v_add_f32_e32 v2, v2, v3
	v_add_f32_e32 v2, v14, v2
	v_cmp_neq_f32_e64 s[4:5], s21, v4
	s_nop 1
	v_cndmask_b32_e64 v2, v22, v2, s[4:5]
	v_cmp_ngt_f32_e64 s[4:5], -1.0, v4
	s_nop 1
	v_cndmask_b32_e64 v2, v23, v2, s[4:5]
	v_cmp_neq_f32_e64 s[4:5], -1.0, v4
	s_nop 1
	v_cndmask_b32_e64 v2, v24, v2, s[4:5]
	v_cmp_lt_f32_e64 s[4:5], |v4|, s22
	s_nop 1
	v_cndmask_b32_e64 v2, v2, v4, s[4:5]
	v_sub_f32_e32 v2, v5, v2
	v_mul_f32_e32 v4, 0x3fb8aa3b, v2
	v_lshl_add_u64 v[2:3], v[16:17], 0, v[8:9]
	global_store_dword v[2:3], v4, off
	s_branch .LBB0_377
